# v33: v32 + MLA tile loop edge: loop increment and next tile's K-fragment address computations moved in front of the per-tile barrier
# baseline (speedup 1.0000x reference)
; #define LAS __attribute__((address_space(3)))
; DI int v_rd_base(int lane) { return ((lane & 3) << 3) | (((lane >> 2) & 3) << 6) | (((lane >> 4) & 1) << 5) | (((lane >> 5) & 1) << 8); }
; #define STAGE_WAIT1() do { if constexpr (NLD == 5) asm volatile("s_waitcnt vmcnt(5)" ::: "memory"); else asm volatile("s_waitcnt vmcnt(4)" ::: "memory"); __builtin_amdgcn_s_barrier(); asm volatile("" ::: "memory"); } while (0)
; #define STAGE_WAIT0() do { asm volatile("s_waitcnt vmcnt(0)" ::: "memory"); __builtin_amdgcn_s_barrier(); asm volatile("" ::: "memory"); } while (0)
;     ...
;     int offK[2], offV[2], offP;
; #pragma unroll
;     for (int i = 0; i < 2; ++i) { const int ob = i * 8192 + wid * 1024 + lane * 16;
;         { const int row = ob >> 8, cb = (ob & 255) ^ ((row & 7) << 4); offK[i] = row * ldk * 2 + cb; }
;         { const int sub = ob >> 9, kk = (sub >> 2) * 8 + ((ob & 511) >> 6), k = (kk & ~0xC) | ((kk & 4) << 1) | ((kk & 8) >> 1), cc = (sub & 3) * 32 + ((ob & 63) >> 1); offV[i] = k * ldv * 2 + cc * 2; } }
;     { const int ob = wid * 1024 + lane * 16, row = ob >> 7, cb = (ob & 127) ^ ((row & 7) << 4); offP = row * 128 + cb; }
;     const int vb0 = (int)(uintptr_t)(lds + SHM_K) + v_rd_base(lane);
;     const int sw_ = (r32 & 7) << 4;
;     const int ka0 = r32 * 256 + ((0 * 32 + hi * 16) ^ sw_), ka1 = r32 * 256 + ((1 * 32 + hi * 16) ^ sw_), ka2 = r32 * 256 + ((2 * 32 + hi * 16) ^ sw_), ka3 = r32 * 256 + ((3 * 32 + hi * 16) ^ sw_);
;     const int pa_0 = r32 * 128 + ((0 * 32 + hi * 16) ^ sw_), pa_1 = r32 * 128 + ((1 * 32 + hi * 16) ^ sw_), pa_2 = r32 * 128 + ((2 * 32 + hi * 16) ^ sw_), pa_3 = r32 * 128 + ((3 * 32 + hi * 16) ^ sw_);
;     ...
;     constexpr int NLD = DPE == 64 ? 5 : 4;
;     ...
;     if constexpr (ABL != 4) { STAGE(0, 0); if (NT > 1) STAGE(1, 1); } if (NT > 1) STAGE_WAIT1(); else STAGE_WAIT0();
;     float m_reg = -1e30f, l_reg = 0.f; f32x16 o[4];
; #pragma unroll
;     for (int d = 0; d < 4; ++d)
; #pragma unroll
;         for (int r = 0; r < 16; ++r) o[d][r] = 0.f;
;     const float thr_raw = 8.0f / scale;
;     int buf = 0;
;     for (int j = 0; j < NT; ++j) {
;         const int bn2 = buf == 0 ? 2 : buf - 1;
;         if constexpr (ABL != 4) { if (j + 2 < NT) STAGE(j + 2, bn2); }
;         if (active && j < wnt) {
;             const LAS unsigned char* Ks = lds + buf * BUF; const LAS unsigned char* Ps = Ks + SHM_K + SHM_V;
.LBB0_1183:
	s_lshl_b32 s26, s55, 2
	s_add_i32 s27, s26, 4
	s_and_b64 s[0:1], s[48:49], exec
	s_cselect_b32 s56, 33, s27
	s_add_i32 s26, s52, s26
	s_and_b64 s[0:1], s[48:49], exec
	v_mul_u32_u24_e32 v2, s54, v252
	s_cselect_b32 s57, 33, s26
	v_readfirstlane_b32 s0, v2
	s_add_u32 s0, s50, s0
	s_addc_u32 s1, s51, 0
	s_lshl_b64 s[0:1], s[0:1], 9
	s_add_u32 s48, s5, s0
	s_addc_u32 s49, s6, s1
	s_lshl_b64 s[26:27], s[50:51], 7
	s_add_u32 s50, s7, s26
	s_addc_u32 s51, s8, s27
	s_and_b32 s55, s58, 0x3fffffc0
	s_lshl_b32 s58, s25, 2
	s_lshl_b32 s60, s25, 1
	s_lshl_b32 s59, s25, 10
	s_and_b32 s58, s58, -16
	s_and_b32 s60, s60, 4
	v_or_b32_e32 v2, s59, v201
	s_or_b32 s60, s58, s60
	v_or_b32_e32 v5, s60, v169
	v_lshrrev_b32_e32 v6, 3, v2
	v_and_b32_e32 v17, 0xc0, v6
	v_lshlrev_b32_e32 v5, 9, v5
	s_add_i32 s58, s59, 0x2000
	v_or3_b32 v6, v5, v17, v170
	v_or_b32_e32 v5, s58, v201
	s_ashr_i32 s58, s58, 8
	s_and_b32 s61, s58, -16
	s_lshr_b32 s58, s58, 1
	v_lshrrev_b32_e32 v7, 4, v5
	s_and_b32 s58, s58, 4
	v_bitop3_b32 v18, v7, v168, s63 bitop3:0x6c
	v_lshlrev_b32_e32 v7, 1, v5
	s_or_b32 s61, s61, s58
	v_and_or_b32 v8, v7, s64, v18
	v_or_b32_e32 v7, s61, v169
	v_lshrrev_b32_e32 v5, 3, v5
	v_and_b32_e32 v5, 0xc0, v5
	v_lshlrev_b32_e32 v7, 9, v7
	v_lshrrev_b32_e32 v4, 4, v2
	v_or3_b32 v10, v7, v5, v170
	v_lshrrev_b32_e32 v5, 7, v201
	v_bitop3_b32 v16, v4, v168, s63 bitop3:0x6c
	v_lshlrev_b32_e32 v4, 1, v2
	v_xor_b32_e32 v5, v5, v187
	v_and_or_b32 v4, v4, s64, v16
	v_lshlrev_b32_e32 v5, 4, v5
	v_and_b32_e32 v14, 0x70, v5
	s_add_i32 s58, s59, 0
	v_ashrrev_i32_e32 v5, 31, v4
	v_lshl_add_u64 v[12:13], s[48:49], 0, v[4:5]
	s_mov_b32 m0, s58
	v_ashrrev_i32_e32 v9, 31, v8
	global_load_lds_dwordx4 v[12:13], off
	v_lshl_add_u64 v[12:13], s[48:49], 0, v[8:9]
	s_add_i32 m0, s58, 0x2000
	v_ashrrev_i32_e32 v7, 31, v6
	global_load_lds_dwordx4 v[12:13], off
	v_lshl_add_u64 v[12:13], s[48:49], 0, v[6:7]
	v_lshl_add_u64 v[12:13], v[12:13], 0, s[66:67]
	s_add_i32 m0, s58, 0x4000
	v_ashrrev_i32_e32 v11, 31, v10
	global_load_lds_dwordx4 v[12:13], off
	v_lshl_add_u64 v[12:13], s[48:49], 0, v[10:11]
	s_lshl_b32 s55, s55, 2
	v_lshl_add_u64 v[12:13], v[12:13], 0, s[66:67]
	s_add_i32 m0, s58, 0x6000
	s_movk_i32 s62, 0xff80
	s_add_i32 s55, s55, 0
	global_load_lds_dwordx4 v[12:13], off
	v_and_or_b32 v12, v2, s62, v14
	s_add_i32 s55, s55, 0x1e000
	v_ashrrev_i32_e32 v13, 31, v12
	s_add_i32 m0, s58, 0x8000
	v_lshl_add_u64 v[14:15], s[50:51], 0, v[12:13]
	s_add_u32 s50, s48, 0x8000
	s_addc_u32 s51, s49, 0
	s_add_u32 s48, s48, 0x8100
	global_load_lds_dwordx4 v[14:15], off
	s_addc_u32 s49, s49, 0
	s_add_i32 m0, s58, 0xa000
	v_lshl_add_u64 v[4:5], s[50:51], 0, v[4:5]
	global_load_lds_dwordx4 v[4:5], off
	v_lshl_add_u64 v[4:5], s[50:51], 0, v[8:9]
	s_add_i32 m0, s58, 0xc000
	v_add_lshl_u32 v2, s61, v169, 9
	global_load_lds_dwordx4 v[4:5], off
	v_lshl_add_u64 v[4:5], s[48:49], 0, v[6:7]
	s_add_i32 m0, s58, 0xe000
	v_add_u32_e32 v6, s59, v181
	global_load_lds_dwordx4 v[4:5], off
	v_lshl_add_u64 v[4:5], s[48:49], 0, v[10:11]
	s_add_i32 m0, s58, 0x10000
	v_mov_b32_e32 v7, v3
	global_load_lds_dwordx4 v[4:5], off
	v_lshl_add_u64 v[4:5], v[14:15], 0, s[68:69]
	s_add_i32 m0, s58, 0x12000
	s_add_u32 s26, s26, 0x28494000
	global_load_lds_dwordx4 v[4:5], off
	v_lshrrev_b32_e32 v4, 3, v6
	s_addc_u32 s27, s27, 0
	v_and_b32_e32 v4, 0xc0, v4
	v_lshl_add_u64 v[152:153], s[26:27], 0, v[12:13]
	s_add_u32 s26, s0, 0x3b1b0100
	v_or3_b32 v4, v170, v2, v4
	s_addc_u32 s27, s1, 0
	v_ashrrev_i32_e32 v5, 31, v4
	v_add_lshl_u32 v2, s60, v169, 9
	v_lshl_add_u64 v[154:155], s[26:27], 0, v[4:5]
	v_or3_b32 v4, v170, v2, v17
	v_ashrrev_i32_e32 v5, 31, v4
	v_lshl_or_b32 v2, s25, 11, v182
	v_lshl_add_u64 v[156:157], s[26:27], 0, v[4:5]
	s_add_u32 s0, s0, 0x3b1b0000
	v_and_or_b32 v4, v2, s64, v16
	s_addc_u32 s1, s1, 0
	v_ashrrev_i32_e32 v5, 31, v4
	v_lshlrev_b32_e32 v2, 1, v6
	v_lshl_add_u64 v[158:159], s[0:1], 0, v[4:5]
	v_and_or_b32 v4, v2, s64, v18
	s_waitcnt vmcnt(5)
	s_barrier
	v_ashrrev_i32_e32 v5, 31, v4
	v_mov_b32_e32 v16, v3
	v_mov_b32_e32 v17, v3
	v_lshl_add_u64 v[160:161], s[0:1], 0, v[4:5]
	v_mov_b32_e32 v2, v3
	v_mov_b32_e32 v4, v3
	v_mov_b32_e32 v5, v3
	v_mov_b32_e32 v6, v3
	v_mov_b32_e32 v8, v3
	v_mov_b32_e32 v9, v3
	v_mov_b32_e32 v10, v3
	v_mov_b32_e32 v11, v3
	v_mov_b32_e32 v12, v3
	v_mov_b32_e32 v13, v3
	v_mov_b32_e32 v14, v3
	v_mov_b32_e32 v15, v3
	v_mov_b64_e32 v[32:33], v[16:17]
	v_mov_b64_e32 v[48:49], v[16:17]
	v_mov_b64_e32 v[64:65], v[16:17]
	v_mov_b64_e32 v[80:81], v[16:17]
	v_lshl_add_u32 v184, v200, 2, s55
	s_mov_b32 s25, 0
	v_mov_b32_e32 v186, 0
	v_mov_b32_e32 v185, 0xf149f2ca
	v_mov_b64_e32 v[30:31], v[14:15]
	v_mov_b64_e32 v[28:29], v[12:13]
	v_mov_b64_e32 v[26:27], v[10:11]
	v_mov_b64_e32 v[24:25], v[8:9]
	v_mov_b64_e32 v[22:23], v[6:7]
	v_mov_b64_e32 v[20:21], v[4:5]
	v_mov_b64_e32 v[18:19], v[2:3]
	v_mov_b64_e32 v[46:47], v[14:15]
	v_mov_b64_e32 v[44:45], v[12:13]
	v_mov_b64_e32 v[42:43], v[10:11]
	v_mov_b64_e32 v[40:41], v[8:9]
	v_mov_b64_e32 v[38:39], v[6:7]
	v_mov_b64_e32 v[36:37], v[4:5]
	v_mov_b64_e32 v[34:35], v[2:3]
	v_mov_b64_e32 v[62:63], v[14:15]
	v_mov_b64_e32 v[60:61], v[12:13]
	v_mov_b64_e32 v[58:59], v[10:11]
	v_mov_b64_e32 v[56:57], v[8:9]
	v_mov_b64_e32 v[54:55], v[6:7]
	v_mov_b64_e32 v[52:53], v[4:5]
	v_mov_b64_e32 v[50:51], v[2:3]
	v_mov_b64_e32 v[78:79], v[14:15]
	v_mov_b64_e32 v[76:77], v[12:13]
	v_mov_b64_e32 v[74:75], v[10:11]
	v_mov_b64_e32 v[72:73], v[8:9]
	v_mov_b64_e32 v[70:71], v[6:7]
	v_mov_b64_e32 v[68:69], v[4:5]
	v_mov_b64_e32 v[66:67], v[2:3]
	s_mul_i32 s0, s25, 0xa000
	s_add_i32 s1, s0, 0x8000
	v_add_u32_e32 v196, s0, v174
	v_add_u32_e32 v197, s0, v175
	v_add_u32_e32 v198, s0, v176
	v_add_u32_e32 v199, s0, v177
	v_add_u32_e32 v162, s1, v172
	v_add_u32_e32 v163, s1, v178
	v_add_u32_e32 v164, s1, v173
	v_add_u32_e32 v165, s1, v179
	s_mov_b32 s26, 0
	s_branch .LBB0_1185
.LBB0_1184:
	s_cmp_eq_u32 s56, s26
	s_cbranch_scc1 .LBB0_1197

; #define LAS __attribute__((address_space(3)))
; #define KRD2(f0, f1, ka_, m_) do { KRD(f0, kbo + ka_, (m_) * 128); KRD(f1, kbo + ka_, (m_) * 128 + 8192); } while (0)
;     ...
;         if constexpr (ABL != 4) { if (j + 2 < NT) STAGE(j + 2, bn2); }
;         if (active && j < wnt) {
;             const LAS unsigned char* Ks = lds + buf * BUF; const LAS unsigned char* Ps = Ks + SHM_K + SHM_V;
;             f32x16 p0, p1;
; #pragma unroll
;             for (int r = 0; r < 16; ++r) { p0[r] = 0.f; p1[r] = 0.f; }
;             if constexpr (ABL != 3) {
;             const int kbo = (int)(uintptr_t)Ks;
;             bf16x8 fa0, fa1, fb0, fb1;
;     ...
;             KRD2(fa0, fa1, ka0, 0); KRD2(fb0, fb1, ka1, 0);
.Latt_qk:
	ds_read_b128 v[4:7], v196 offset:0
	ds_read_b128 v[8:11], v196 offset:8192
	ds_read_b128 v[12:15], v197 offset:0
	ds_read_b128 v[188:191], v197 offset:8192
	ds_read_b128 v[192:195], v198 offset:0
	ds_read_b128 v[214:217], v198 offset:8192
	ds_read_b128 v[218:221], v199 offset:0
	ds_read_b128 v[234:237], v199 offset:8192
	s_and_b64 vcc, exec, s[48:49]
	s_cbranch_vccnz .Latt_nostage
	s_add_i32 s0, s27, 0xffff6000
	s_cmp_lg_u32 s25, 0
	s_cselect_b32 s0, s0, 0x14000
	s_add_i32 s0, s58, s0
	v_lshl_add_u64 v[16:17], s[34:35], 0, v[158:159]
	s_mov_b32 m0, s0
	s_nop 0
	global_load_lds_dwordx4 v[16:17], off
	v_lshl_add_u64 v[16:17], s[34:35], 0, v[160:161]
	s_add_i32 m0, s0, 0x2000
	s_nop 0
	global_load_lds_dwordx4 v[16:17], off
	v_lshl_add_u64 v[16:17], s[34:35], 0, v[156:157]
	s_add_i32 m0, s0, 0x4000
	s_nop 0
	global_load_lds_dwordx4 v[16:17], off
	v_lshl_add_u64 v[16:17], s[34:35], 0, v[154:155]
	s_add_i32 m0, s0, 0x6000
	s_nop 0
	global_load_lds_dwordx4 v[16:17], off
	v_lshl_add_u64 v[16:17], s[34:35], 0, v[152:153]
	s_add_i32 m0, s0, 0x8000
	s_nop 0
	global_load_lds_dwordx4 v[16:17], off

; #define LAS __attribute__((address_space(3)))
; #define STAGE_WAIT1() do { if constexpr (NLD == 5) asm volatile("s_waitcnt vmcnt(5)" ::: "memory"); else asm volatile("s_waitcnt vmcnt(4)" ::: "memory"); __builtin_amdgcn_s_barrier(); asm volatile("" ::: "memory"); } while (0)
; #define STAGE_WAIT0() do { asm volatile("s_waitcnt vmcnt(0)" ::: "memory"); __builtin_amdgcn_s_barrier(); asm volatile("" ::: "memory"); } while (0)
;     ...
;     for (int j = 0; j < NT; ++j) {
;         const int bn2 = buf == 0 ? 2 : buf - 1;
;         if constexpr (ABL != 4) { if (j + 2 < NT) STAGE(j + 2, bn2); }
;         if (active && j < wnt) {
;             const LAS unsigned char* Ks = lds + buf * BUF; const LAS unsigned char* Ps = Ks + SHM_K + SHM_V;
;             f32x16 p0, p1;
; #pragma unroll
;             for (int r = 0; r < 16; ++r) { p0[r] = 0.f; p1[r] = 0.f; }
;             if constexpr (ABL != 3) {
;             const int kbo = (int)(uintptr_t)Ks;
;     ...
;         asm volatile("s_waitcnt lgkmcnt(0)" ::: "memory");
;         if (j + 2 < NT) STAGE_WAIT1(); else STAGE_WAIT0();
;         buf = buf == 2 ? 0 : buf + 1;
.LBB0_1193:
	s_add_i32 s0, s25, 1
	s_cmp_lg_u32 s25, 2
	s_cselect_b32 s25, s0, 0
	s_add_i32 s26, s26, 1
	v_lshl_add_u64 v[152:153], v[152:153], 0, s[68:69]
	v_lshl_add_u64 v[154:155], v[154:155], 0, s[22:23]
	v_lshl_add_u64 v[156:157], v[156:157], 0, s[22:23]
	v_lshl_add_u64 v[158:159], v[158:159], 0, s[22:23]
	v_lshl_add_u64 v[160:161], v[160:161], 0, s[22:23]
	s_mul_i32 s0, s25, 0xa000
	s_add_i32 s1, s0, 0x8000
	v_add_u32_e32 v196, s0, v174
	v_add_u32_e32 v197, s0, v175
	v_add_u32_e32 v198, s0, v176
	v_add_u32_e32 v199, s0, v177
	v_add_u32_e32 v162, s1, v172
	v_add_u32_e32 v163, s1, v178
	v_add_u32_e32 v164, s1, v173
	v_add_u32_e32 v165, s1, v179
	s_waitcnt lgkmcnt(0)
	s_mov_b64 s[0:1], -1
	s_and_b64 vcc, exec, s[48:49]
	s_cbranch_vccz .LBB0_1195
	s_waitcnt vmcnt(0)
	s_barrier
	s_mov_b64 s[0:1], 0

; #define PG8_STAGE(bufoff, gbase, voff) do { _Pragma("unroll") for (int _i = 0; _i < 2; ++_i) \
;         __builtin_amdgcn_global_load_lds((const unsigned*)((const char*)(gbase) + (voff)[_i]), (PG8_LAS unsigned*)(lds + (bufoff) + ldsw + _i * 8192), 16, 0, 0); } while (0)
; #define PG8_LDA(dst, b, h) do { _Pragma("unroll") for (int m = 0; m < 4; ++m) _Pragma("unroll") for (int k = 0; k < 2; ++k) dst[m][k] = *(const PG8_LAS bf16x8*)(lds + PG8_SA(b, h) + aoff + m * 2048 + k * 1024); } while (0)
; #define PG8_LDB(dst, b, h) do { _Pragma("unroll") for (int n = 0; n < 2; ++n) _Pragma("unroll") for (int k = 0; k < 2; ++k) dst[n][k] = *(const PG8_LAS bf16x8*)(lds + PG8_SB(b, h) + boff + n * 2048 + k * 1024); } while (0)
; #define PG8_MMA(ai, bj, At, Bt) do { __builtin_amdgcn_s_setprio(1); _Pragma("unroll") for (int m = 0; m < 4; ++m) _Pragma("unroll") for (int n = 0; n < 2; ++n) _Pragma("unroll") for (int k = 0; k < 2; ++k) \
;         acc[ai][bj][m][n] = __builtin_amdgcn_mfma_f32_16x16x32_bf16(Bt[n][k], At[m][k], acc[ai][bj][m][n], 0, 0, 0); __builtin_amdgcn_s_setprio(0); } while (0)
; #define PG8_WAIT_V(n) asm volatile("s_waitcnt vmcnt(" #n ")" ::: "memory")
; #define PG8_WAIT_L(n) asm volatile("s_waitcnt lgkmcnt(" #n ")" ::: "memory")
; #define PG8_BAR __builtin_amdgcn_s_barrier()
; #define PG8_SCHED __builtin_amdgcn_sched_barrier(0)
; template <class Epi, class Sched, bool ALIGN_EPI = false, bool SP2 = false>
; __device__ __forceinline__ void gemm_phase(PG8_LAS unsigned char* lds, const Gemm g, const Sched& S, const Epi& E) {
;     ...
;             PG8_LDB(B0, 0, 0); PG8_LDB(B1, 0, 1); PG8_SCHED; PG8_LDA(At, 0, 0); PG8_STAGE(PG8_SA(1, 1), a1 + hstep, voffA);
;             PG8_WAIT_V(8); PG8_WAIT_L(0); PG8_BAR; PG8_MMA(0, 0, At, B0); PG8_MMA(0, 1, At, B1); PG8_BAR; PG8_SCHED;
;             PG8_LDA(At, 0, 1); PG8_STAGE(PG8_SB(0, 0), b2, voffB); PG8_STAGE(PG8_SB(0, 1), b2 + hstep, voffB); PG8_STAGE(PG8_SA(0, 0), a2, voffA);
;             PG8_WAIT_V(8); PG8_WAIT_L(0); PG8_BAR; PG8_MMA(1, 0, At, B0); PG8_MMA(1, 1, At, B1); PG8_BAR; PG8_SCHED;
.LBB0_1624:
	s_setprio 0
	ds_read_b128 v[142:145], v210
	ds_read_b128 v[150:153], v210 offset:1024
	ds_read_b128 v[154:157], v210 offset:2048
	ds_read_b128 v[158:161], v210 offset:3072
	ds_read_b128 v[162:165], v210 offset:16384
	ds_read_b128 v[166:169], v210 offset:17408
	ds_read_b128 v[170:173], v210 offset:18432
	ds_read_b128 v[174:177], v210 offset:19456
	ds_read_b128 v[178:181], v149
	ds_read_b128 v[182:185], v149 offset:1024
	ds_read_b128 v[186:189], v149 offset:2048
	ds_read_b128 v[190:193], v149 offset:3072
	ds_read_b128 v[194:197], v149 offset:4096
	ds_read_b128 v[198:201], v149 offset:5120
	ds_read_b128 v[202:205], v149 offset:6144
	ds_read_b128 v[206:209], v149 offset:7168
	s_add_u32 s0, s56, 0xfff00080
	s_addc_u32 s1, s57, -1
	s_add_i32 s63, 0, 0x10000
	s_cmp_eq_u32 s62, 60
	s_cselect_b32 s27, s51, s1
	s_cselect_b32 s26, s50, s0
	s_cselect_b32 s1, s53, s49
	s_cselect_b32 s0, s52, s47
	s_add_i32 s66, 0, 0x14000
	s_add_u32 s100, s56, 0xfff00000
	s_addc_u32 s101, s57, -1
	s_mov_b32 m0, s58
	s_nop 0
	global_load_lds_dwordx4 v132, s[100:101]
	s_mov_b32 m0, s59
	s_nop 0
	global_load_lds_dwordx4 v134, s[100:101]
	s_add_i32 m0, s10, 0xc000
	s_nop 0
	global_load_lds_dwordx4 v138, s[56:57]
	s_add_i32 m0, s10, 0xe000
	s_nop 0
	global_load_lds_dwordx4 v140, s[56:57]
	s_nop 0
	s_nop 0
	s_nop 0
	s_setprio 1
	s_waitcnt vmcnt(8)
	s_waitcnt lgkmcnt(0)
	s_barrier
	v_mfma_f32_16x16x32_bf16 v[128:131], v[142:145], v[178:181], v[128:131]
	v_mfma_f32_16x16x32_bf16 v[128:131], v[150:153], v[182:185], v[128:131]
	v_mfma_f32_16x16x32_bf16 v[124:127], v[154:157], v[178:181], v[124:127]
	v_mfma_f32_16x16x32_bf16 v[124:127], v[158:161], v[182:185], v[124:127]
	v_mfma_f32_16x16x32_bf16 v[108:111], v[154:157], v[186:189], v[108:111]
	v_mfma_f32_16x16x32_bf16 v[108:111], v[158:161], v[190:193], v[108:111]
	v_mfma_f32_16x16x32_bf16 v[112:115], v[142:145], v[186:189], v[112:115]
	v_mfma_f32_16x16x32_bf16 v[112:115], v[150:153], v[190:193], v[112:115]
	v_mfma_f32_16x16x32_bf16 v[96:99], v[142:145], v[194:197], v[96:99]
	v_mfma_f32_16x16x32_bf16 v[96:99], v[150:153], v[198:201], v[96:99]
	v_mfma_f32_16x16x32_bf16 v[92:95], v[154:157], v[194:197], v[92:95]
	v_mfma_f32_16x16x32_bf16 v[92:95], v[158:161], v[198:201], v[92:95]
	v_mfma_f32_16x16x32_bf16 v[76:79], v[154:157], v[202:205], v[76:79]
	v_mfma_f32_16x16x32_bf16 v[76:79], v[158:161], v[206:209], v[76:79]
	v_mfma_f32_16x16x32_bf16 v[80:83], v[142:145], v[202:205], v[80:83]
	v_mfma_f32_16x16x32_bf16 v[80:83], v[150:153], v[206:209], v[80:83]
	s_setprio 0
	s_setprio 1
	v_mfma_f32_16x16x32_bf16 v[120:123], v[162:165], v[178:181], v[120:123]
	v_mfma_f32_16x16x32_bf16 v[120:123], v[166:169], v[182:185], v[120:123]
	v_mfma_f32_16x16x32_bf16 v[116:119], v[170:173], v[178:181], v[116:119]
	v_mfma_f32_16x16x32_bf16 v[116:119], v[174:177], v[182:185], v[116:119]
	v_mfma_f32_16x16x32_bf16 v[100:103], v[170:173], v[186:189], v[100:103]
	v_mfma_f32_16x16x32_bf16 v[100:103], v[174:177], v[190:193], v[100:103]
	v_mfma_f32_16x16x32_bf16 v[104:107], v[162:165], v[186:189], v[104:107]
	v_mfma_f32_16x16x32_bf16 v[104:107], v[166:169], v[190:193], v[104:107]
	v_mfma_f32_16x16x32_bf16 v[88:91], v[162:165], v[194:197], v[88:91]
	v_mfma_f32_16x16x32_bf16 v[88:91], v[166:169], v[198:201], v[88:91]
	v_mfma_f32_16x16x32_bf16 v[84:87], v[170:173], v[194:197], v[84:87]
	v_mfma_f32_16x16x32_bf16 v[84:87], v[174:177], v[198:201], v[84:87]
	v_mfma_f32_16x16x32_bf16 v[68:71], v[170:173], v[202:205], v[68:71]
	v_mfma_f32_16x16x32_bf16 v[68:71], v[174:177], v[206:209], v[68:71]
	v_mfma_f32_16x16x32_bf16 v[72:75], v[162:165], v[202:205], v[72:75]
	v_mfma_f32_16x16x32_bf16 v[72:75], v[166:169], v[206:209], v[72:75]
	s_barrier
	s_setprio 0
	ds_read_b128 v[178:181], v149 offset:16384
	ds_read_b128 v[182:185], v149 offset:17408
	ds_read_b128 v[186:189], v149 offset:18432
	ds_read_b128 v[190:193], v149 offset:19456
	ds_read_b128 v[194:197], v149 offset:20480
	ds_read_b128 v[198:201], v149 offset:21504
	ds_read_b128 v[202:205], v149 offset:22528
	ds_read_b128 v[206:209], v149 offset:23552
	s_add_i32 s63, s63, s9
	s_mov_b32 m0, s63
	s_nop 0
	global_load_lds_dwordx4 v2, s[0:1]
	s_add_i32 m0, s63, 0x2000
	s_add_u32 s64, s0, 0x100000
	s_addc_u32 s65, s1, 0
	s_add_i32 s63, s66, s9
	global_load_lds_dwordx4 v136, s[0:1]
	s_mov_b32 m0, s63
	s_nop 0
	global_load_lds_dwordx4 v2, s[64:65]
	s_add_i32 m0, s63, 0x2000
	s_nop 0
	global_load_lds_dwordx4 v136, s[64:65]
	s_setprio 1
	s_waitcnt vmcnt(6)
	s_waitcnt lgkmcnt(0)
	s_barrier
	v_mfma_f32_16x16x32_bf16 v[64:67], v[142:145], v[178:181], v[64:67]
	v_mfma_f32_16x16x32_bf16 v[64:67], v[150:153], v[182:185], v[64:67]
	v_mfma_f32_16x16x32_bf16 v[60:63], v[154:157], v[178:181], v[60:63]
	v_mfma_f32_16x16x32_bf16 v[60:63], v[158:161], v[182:185], v[60:63]
	v_mfma_f32_16x16x32_bf16 v[44:47], v[154:157], v[186:189], v[44:47]
	v_mfma_f32_16x16x32_bf16 v[44:47], v[158:161], v[190:193], v[44:47]
	v_mfma_f32_16x16x32_bf16 v[48:51], v[142:145], v[186:189], v[48:51]
	v_mfma_f32_16x16x32_bf16 v[48:51], v[150:153], v[190:193], v[48:51]
	v_mfma_f32_16x16x32_bf16 v[32:35], v[142:145], v[194:197], v[32:35]
	v_mfma_f32_16x16x32_bf16 v[32:35], v[150:153], v[198:201], v[32:35]
	v_mfma_f32_16x16x32_bf16 v[28:31], v[154:157], v[194:197], v[28:31]
	v_mfma_f32_16x16x32_bf16 v[28:31], v[158:161], v[198:201], v[28:31]
	v_mfma_f32_16x16x32_bf16 v[12:15], v[154:157], v[202:205], v[12:15]
	v_mfma_f32_16x16x32_bf16 v[12:15], v[158:161], v[206:209], v[12:15]
	v_mfma_f32_16x16x32_bf16 v[16:19], v[142:145], v[202:205], v[16:19]
	v_mfma_f32_16x16x32_bf16 v[16:19], v[150:153], v[206:209], v[16:19]
	s_setprio 0
	s_setprio 1
	v_mfma_f32_16x16x32_bf16 v[56:59], v[162:165], v[178:181], v[56:59]
	v_mfma_f32_16x16x32_bf16 v[56:59], v[166:169], v[182:185], v[56:59]
	v_mfma_f32_16x16x32_bf16 v[52:55], v[170:173], v[178:181], v[52:55]
	v_mfma_f32_16x16x32_bf16 v[52:55], v[174:177], v[182:185], v[52:55]
	v_mfma_f32_16x16x32_bf16 v[36:39], v[170:173], v[186:189], v[36:39]
	v_mfma_f32_16x16x32_bf16 v[36:39], v[174:177], v[190:193], v[36:39]
	v_mfma_f32_16x16x32_bf16 v[40:43], v[162:165], v[186:189], v[40:43]
	v_mfma_f32_16x16x32_bf16 v[40:43], v[166:169], v[190:193], v[40:43]
	v_mfma_f32_16x16x32_bf16 v[24:27], v[162:165], v[194:197], v[24:27]
	v_mfma_f32_16x16x32_bf16 v[24:27], v[166:169], v[198:201], v[24:27]
	v_mfma_f32_16x16x32_bf16 v[20:23], v[170:173], v[194:197], v[20:23]
	v_mfma_f32_16x16x32_bf16 v[20:23], v[174:177], v[198:201], v[20:23]
	v_mfma_f32_16x16x32_bf16 v[4:7], v[170:173], v[202:205], v[4:7]
	v_mfma_f32_16x16x32_bf16 v[4:7], v[174:177], v[206:209], v[4:7]
	v_mfma_f32_16x16x32_bf16 v[8:11], v[162:165], v[202:205], v[8:11]
	v_mfma_f32_16x16x32_bf16 v[8:11], v[166:169], v[206:209], v[8:11]
	s_barrier
; #define PG8_STAGE(bufoff, gbase, voff) do { _Pragma("unroll") for (int _i = 0; _i < 2; ++_i) \
;         __builtin_amdgcn_global_load_lds((const unsigned*)((const char*)(gbase) + (voff)[_i]), (PG8_LAS unsigned*)(lds + (bufoff) + ldsw + _i * 8192), 16, 0, 0); } while (0)
; #define PG8_LDA(dst, b, h) do { _Pragma("unroll") for (int m = 0; m < 4; ++m) _Pragma("unroll") for (int k = 0; k < 2; ++k) dst[m][k] = *(const PG8_LAS bf16x8*)(lds + PG8_SA(b, h) + aoff + m * 2048 + k * 1024); } while (0)
; #define PG8_LDB(dst, b, h) do { _Pragma("unroll") for (int n = 0; n < 2; ++n) _Pragma("unroll") for (int k = 0; k < 2; ++k) dst[n][k] = *(const PG8_LAS bf16x8*)(lds + PG8_SB(b, h) + boff + n * 2048 + k * 1024); } while (0)
; #define PG8_MMA(ai, bj, At, Bt) do { __builtin_amdgcn_s_setprio(1); _Pragma("unroll") for (int m = 0; m < 4; ++m) _Pragma("unroll") for (int n = 0; n < 2; ++n) _Pragma("unroll") for (int k = 0; k < 2; ++k) \
;         acc[ai][bj][m][n] = __builtin_amdgcn_mfma_f32_16x16x32_bf16(Bt[n][k], At[m][k], acc[ai][bj][m][n], 0, 0, 0); __builtin_amdgcn_s_setprio(0); } while (0)
; #define PG8_WAIT_V(n) asm volatile("s_waitcnt vmcnt(" #n ")" ::: "memory")
; #define PG8_WAIT_L(n) asm volatile("s_waitcnt lgkmcnt(" #n ")" ::: "memory")
; #define PG8_BAR __builtin_amdgcn_s_barrier()
; #define PG8_SCHED __builtin_amdgcn_sched_barrier(0)
; template <class Epi, class Sched, bool ALIGN_EPI = false, bool SP2 = false>
; __device__ __forceinline__ void gemm_phase(PG8_LAS unsigned char* lds, const Gemm g, const Sched& S, const Epi& E) {
;     ...
;         for (int t = 0; t < nt; t += 2) {
;             const bool last = (t == nt - 2);
;             const char* a1 = cA + (size_t)(t + 1) * kstep;
;             const char* a2 = last ? nA : cA + (size_t)(t + 2) * kstep; const char* b2 = last ? nB : cB + (size_t)(t + 2) * kstep;
;     ...
;             PG8_LDB(B0, 1, 0); PG8_LDB(B1, 1, 1); PG8_SCHED; PG8_LDA(At, 1, 0); PG8_STAGE(PG8_SA(0, 1), a2 + hstep, voffA);
;             PG8_WAIT_V(8); PG8_WAIT_L(0); PG8_BAR; PG8_MMA(0, 0, At, B0); PG8_MMA(0, 1, At, B1); PG8_BAR; PG8_SCHED;
;             PG8_LDA(At, 1, 1); PG8_STAGE(PG8_SB(1, 0), b3, voffB); PG8_STAGE(PG8_SB(1, 1), b3 + hstep, voffB); PG8_STAGE(PG8_SA(1, 0), a3, voffA);
;             PG8_WAIT_V(8); PG8_WAIT_L(0); PG8_BAR; PG8_MMA(1, 0, At, B0); PG8_MMA(1, 1, At, B1); PG8_BAR; PG8_SCHED;
	s_setprio 0
	ds_read_b128 v[142:145], v210 offset:32768
	ds_read_b128 v[150:153], v210 offset:33792
	ds_read_b128 v[154:157], v210 offset:34816
	ds_read_b128 v[158:161], v210 offset:35840
	ds_read_b128 v[162:165], v210 offset:49152
	ds_read_b128 v[166:169], v210 offset:50176
	ds_read_b128 v[170:173], v210 offset:51200
	ds_read_b128 v[174:177], v210 offset:52224
	ds_read_b128 v[178:181], v149 offset:32768
	ds_read_b128 v[182:185], v149 offset:33792
	ds_read_b128 v[186:189], v149 offset:34816
	ds_read_b128 v[190:193], v149 offset:35840
	ds_read_b128 v[194:197], v149 offset:36864
	ds_read_b128 v[198:201], v149 offset:37888
	ds_read_b128 v[202:205], v149 offset:38912
	ds_read_b128 v[206:209], v149 offset:39936
	s_add_i32 s63, 0, 0x18000
	s_add_i32 s64, 0, 0x1c000
	s_mov_b32 m0, s10
	s_nop 0
	global_load_lds_dwordx4 v132, s[26:27]
	s_mov_b32 m0, s11
	s_nop 0
	global_load_lds_dwordx4 v134, s[26:27]
	s_add_u32 s26, s26, 0x100000
	s_addc_u32 s27, s27, 0
	s_mov_b32 m0, s25
	s_nop 0
	global_load_lds_dwordx4 v132, s[26:27]
	s_mov_b32 m0, s55
	s_nop 0
	global_load_lds_dwordx4 v134, s[26:27]
	s_nop 0
	s_setprio 1
	s_waitcnt vmcnt(8)
	s_waitcnt lgkmcnt(0)
	s_barrier
	v_mfma_f32_16x16x32_bf16 v[128:131], v[142:145], v[178:181], v[128:131]
	v_mfma_f32_16x16x32_bf16 v[128:131], v[150:153], v[182:185], v[128:131]
	v_mfma_f32_16x16x32_bf16 v[124:127], v[154:157], v[178:181], v[124:127]
	v_mfma_f32_16x16x32_bf16 v[124:127], v[158:161], v[182:185], v[124:127]
	v_mfma_f32_16x16x32_bf16 v[108:111], v[154:157], v[186:189], v[108:111]
	v_mfma_f32_16x16x32_bf16 v[108:111], v[158:161], v[190:193], v[108:111]
	v_mfma_f32_16x16x32_bf16 v[112:115], v[142:145], v[186:189], v[112:115]
	v_mfma_f32_16x16x32_bf16 v[112:115], v[150:153], v[190:193], v[112:115]
	v_mfma_f32_16x16x32_bf16 v[96:99], v[142:145], v[194:197], v[96:99]
	v_mfma_f32_16x16x32_bf16 v[96:99], v[150:153], v[198:201], v[96:99]
	v_mfma_f32_16x16x32_bf16 v[92:95], v[154:157], v[194:197], v[92:95]
	v_mfma_f32_16x16x32_bf16 v[92:95], v[158:161], v[198:201], v[92:95]
	v_mfma_f32_16x16x32_bf16 v[76:79], v[154:157], v[202:205], v[76:79]
	v_mfma_f32_16x16x32_bf16 v[76:79], v[158:161], v[206:209], v[76:79]
	v_mfma_f32_16x16x32_bf16 v[80:83], v[142:145], v[202:205], v[80:83]
	v_mfma_f32_16x16x32_bf16 v[80:83], v[150:153], v[206:209], v[80:83]
	s_setprio 0
	s_setprio 1
	v_mfma_f32_16x16x32_bf16 v[120:123], v[162:165], v[178:181], v[120:123]
	v_mfma_f32_16x16x32_bf16 v[120:123], v[166:169], v[182:185], v[120:123]
	v_mfma_f32_16x16x32_bf16 v[116:119], v[170:173], v[178:181], v[116:119]
	v_mfma_f32_16x16x32_bf16 v[116:119], v[174:177], v[182:185], v[116:119]
	v_mfma_f32_16x16x32_bf16 v[100:103], v[170:173], v[186:189], v[100:103]
	v_mfma_f32_16x16x32_bf16 v[100:103], v[174:177], v[190:193], v[100:103]
	v_mfma_f32_16x16x32_bf16 v[104:107], v[162:165], v[186:189], v[104:107]
	v_mfma_f32_16x16x32_bf16 v[104:107], v[166:169], v[190:193], v[104:107]
	v_mfma_f32_16x16x32_bf16 v[88:91], v[162:165], v[194:197], v[88:91]
	v_mfma_f32_16x16x32_bf16 v[88:91], v[166:169], v[198:201], v[88:91]
	v_mfma_f32_16x16x32_bf16 v[84:87], v[170:173], v[194:197], v[84:87]
	v_mfma_f32_16x16x32_bf16 v[84:87], v[174:177], v[198:201], v[84:87]
	v_mfma_f32_16x16x32_bf16 v[68:71], v[170:173], v[202:205], v[68:71]
	v_mfma_f32_16x16x32_bf16 v[68:71], v[174:177], v[206:209], v[68:71]
	v_mfma_f32_16x16x32_bf16 v[72:75], v[162:165], v[202:205], v[72:75]
	v_mfma_f32_16x16x32_bf16 v[72:75], v[166:169], v[206:209], v[72:75]
	s_barrier
	s_setprio 0
	ds_read_b128 v[178:181], v149 offset:49152
	ds_read_b128 v[182:185], v149 offset:50176
	ds_read_b128 v[186:189], v149 offset:51200
	ds_read_b128 v[190:193], v149 offset:52224
	ds_read_b128 v[194:197], v149 offset:53248
	ds_read_b128 v[198:201], v149 offset:54272
	ds_read_b128 v[202:205], v149 offset:55296
	ds_read_b128 v[206:209], v149 offset:56320
	s_add_i32 s26, s63, s9
	s_mov_b32 m0, s26
	s_add_u32 s0, s0, 0x80
	s_addc_u32 s1, s1, 0
	global_load_lds_dwordx4 v2, s[0:1]
	s_add_i32 m0, s26, 0x2000
	s_add_i32 s26, s64, s9
	global_load_lds_dwordx4 v136, s[0:1]
	s_add_u32 s0, s0, 0x100000
	s_addc_u32 s1, s1, 0
	s_mov_b32 m0, s26
	s_nop 0
	global_load_lds_dwordx4 v2, s[0:1]
	s_add_i32 m0, s26, 0x2000
	s_nop 0
	global_load_lds_dwordx4 v136, s[0:1]
	s_setprio 1
	s_waitcnt vmcnt(6)
	s_waitcnt lgkmcnt(0)
	s_barrier
	v_mfma_f32_16x16x32_bf16 v[64:67], v[142:145], v[178:181], v[64:67]
	v_mfma_f32_16x16x32_bf16 v[64:67], v[150:153], v[182:185], v[64:67]
	v_mfma_f32_16x16x32_bf16 v[60:63], v[154:157], v[178:181], v[60:63]
	v_mfma_f32_16x16x32_bf16 v[60:63], v[158:161], v[182:185], v[60:63]
	v_mfma_f32_16x16x32_bf16 v[44:47], v[154:157], v[186:189], v[44:47]
	v_mfma_f32_16x16x32_bf16 v[44:47], v[158:161], v[190:193], v[44:47]
	v_mfma_f32_16x16x32_bf16 v[48:51], v[142:145], v[186:189], v[48:51]
	v_mfma_f32_16x16x32_bf16 v[48:51], v[150:153], v[190:193], v[48:51]
	v_mfma_f32_16x16x32_bf16 v[32:35], v[142:145], v[194:197], v[32:35]
	v_mfma_f32_16x16x32_bf16 v[32:35], v[150:153], v[198:201], v[32:35]
	v_mfma_f32_16x16x32_bf16 v[28:31], v[154:157], v[194:197], v[28:31]
	v_mfma_f32_16x16x32_bf16 v[28:31], v[158:161], v[198:201], v[28:31]
	v_mfma_f32_16x16x32_bf16 v[12:15], v[154:157], v[202:205], v[12:15]
	v_mfma_f32_16x16x32_bf16 v[12:15], v[158:161], v[206:209], v[12:15]
	v_mfma_f32_16x16x32_bf16 v[16:19], v[142:145], v[202:205], v[16:19]
	v_mfma_f32_16x16x32_bf16 v[16:19], v[150:153], v[206:209], v[16:19]
	s_setprio 0
	s_setprio 1
	s_add_i32 s62, s62, 2
	s_add_u32 s56, s56, 0x100
	s_addc_u32 s57, s57, 0
	s_add_u32 s47, s47, 0x100
	s_addc_u32 s49, s49, 0
	s_nop 0
	v_mfma_f32_16x16x32_bf16 v[56:59], v[162:165], v[178:181], v[56:59]
	v_mfma_f32_16x16x32_bf16 v[56:59], v[166:169], v[182:185], v[56:59]
	v_mfma_f32_16x16x32_bf16 v[52:55], v[170:173], v[178:181], v[52:55]
	v_mfma_f32_16x16x32_bf16 v[52:55], v[174:177], v[182:185], v[52:55]
	v_mfma_f32_16x16x32_bf16 v[36:39], v[170:173], v[186:189], v[36:39]
	v_mfma_f32_16x16x32_bf16 v[36:39], v[174:177], v[190:193], v[36:39]
	v_mfma_f32_16x16x32_bf16 v[40:43], v[162:165], v[186:189], v[40:43]
	v_mfma_f32_16x16x32_bf16 v[40:43], v[166:169], v[190:193], v[40:43]
	v_mfma_f32_16x16x32_bf16 v[24:27], v[162:165], v[194:197], v[24:27]
	v_mfma_f32_16x16x32_bf16 v[24:27], v[166:169], v[198:201], v[24:27]
	v_mfma_f32_16x16x32_bf16 v[20:23], v[170:173], v[194:197], v[20:23]
	v_mfma_f32_16x16x32_bf16 v[20:23], v[174:177], v[198:201], v[20:23]
	v_mfma_f32_16x16x32_bf16 v[4:7], v[170:173], v[202:205], v[4:7]
	v_mfma_f32_16x16x32_bf16 v[4:7], v[174:177], v[206:209], v[4:7]
	v_mfma_f32_16x16x32_bf16 v[8:11], v[162:165], v[202:205], v[8:11]
	v_mfma_f32_16x16x32_bf16 v[8:11], v[166:169], v[206:209], v[8:11]
	s_barrier
	s_cmp_gt_u32 s62, 61
	s_cbranch_scc0 .LBB0_1624
	s_setprio 0
	s_and_b64 vcc, exec, s[44:45]
	s_cbranch_vccz .LBB0_1627
	s_barrier
